# combo7 + s_setprio 2 around the phase-B in-proj tile k-loop
# speedup vs baseline: 1.0110x; 1.0007x over previous
; DI char* opq(char* q) { size_t z = 0; asm volatile("" : "+s"(z)); return q + z; }
; DI int tidx() { int t = threadIdx.x; asm volatile("" : "+v"(t)); return t; }
; #define GLOAD(dst, kt_) _Pragma("unroll") for (int i = 0; i < NCH; ++i) { dst[i] = (i < NCHW) ? ldw(i, tid >> 3, (kt_) * 64 + (tid & 7) * 8) : ldx(i - NCHW, tid >> 3, (kt_) * 64 + (tid & 7) * 8); }
; #define LSTORE(src, base) _Pragma("unroll") for (int i = 0; i < NCH; ++i) { const int c = tid + 256 * i; *(u32x4*)((base) + (c >> 3) * 144 + (c & 7) * 16) = src[i]; }
; template <int WGN, int INS, int IMS, bool DB, class LdW, class LdX>
; DI void gemm_core(f32x16 (&acc)[INS][IMS], const int KT, LdW ldw, LdX ldx, char* lds, const int tid) {
;   constexpr int WGM = 4 / WGN;
;   constexpr int WROWS = WGN * 32 * INS, XROWS = WGM * 32 * IMS, NROWS = WROWS + XROWS, NCH = NROWS / 32, NCHW = WROWS / 32, BUFB = NROWS * 144;
;   const int lane = tid & 63, wid = tid >> 6, l31 = lane & 31, hi = lane >> 5;
;   const int wn = (WGN == 2) ? (wid >> 1) : wid, wm = (WGN == 2) ? (wid & 1) : 0;
;   const int offa = (wn * 32 * INS + l31) * 144 + hi * 16;
;   const int offb = (WROWS + wm * 32 * IMS + l31) * 144 + hi * 16;
; #pragma unroll
;   for (int a = 0; a < INS; ++a)
; #pragma unroll
;     for (int b = 0; b < IMS; ++b)
; #pragma unroll
;       for (int r = 0; r < 16; ++r) acc[a][b][r] = 0.f;
;     ...
;   if (DB) {
;     u32x4 preA[NCH], preB[NCH];
;     GLOAD(preA, 0)
;     GLOAD(preB, 1)
;     __syncthreads();
;     LSTORE(preA, lds)
;     __syncthreads();
; template <int NTW>
; DI void inproj_tile(const Params& p, int l, int mt, int ntile, char* lds) {
;   char* const ws_ = opq(p.ws);
;   const u16* W = (const u16*)(ws_ + OFF_WIN) + ((size_t)l * NP + ntile * 64 * NTW) * 1024;
;   const u16* X = (const u16*)(ws_ + OFF_XB) + (size_t)mt * 128 * 1024;
;   f32x16 acc[NTW][2];
;   const int tid = tidx();
;   gemm_core<2, NTW, 2, (NTW == 2)>(acc, 16, [&](int i, int r0, int k) -> u32x4 { return *(const u32x4*)((W + i * 32768) + (unsigned)(r0 * 1024 + k)); },
;                [&](int i, int r0, int k) -> u32x4 { return *(const u32x4*)((X + i * 32768) + (unsigned)(r0 * 1024 + k)); }, lds, tid);
.Lb_tile:
	s_lshl_b32 s0, s36, 4
	s_and_b32 s0, s0, 0x70
	s_bfe_u32 s1, s36, 0x40003
	s_or_b32 s4, s0, s1
	s_mov_b64 s[0:1], 0
	s_add_u32 s27, s90, s0
	s_addc_u32 s37, s91, s1
	s_lshl_b32 s0, s36, 1
	s_and_b32 s0, s0, 0xffffff00
	s_addk_i32 s0, 0x800
	s_ashr_i32 s1, s0, 31
	s_add_u32 s2, s0, s28
	s_addc_u32 s3, s1, 0
	s_lshl_b64 s[2:3], s[2:3], 11
	s_add_u32 s2, s27, s2
	s_addc_u32 s3, s37, s3
	s_lshl_b32 s80, s4, 7
	s_lshl_b32 s26, s4, 18
	s_add_u32 s24, s27, s26
	s_addc_u32 s25, s37, 0
	s_add_u32 s4, s24, 0x2a40000
	s_addc_u32 s5, s25, 0
	v_mov_b32_e32 v181, v176
	v_and_b32_e32 v183, 0x5f, v181
	v_lshrrev_b32_e32 v185, 3, v181
	v_or_b32_e32 v254, s80, v183
	v_lshlrev_b32_e32 v254, 2, v254
	s_add_u32 s14, s27, 0x4a40000
	s_addc_u32 s15, s37, 0
	global_load_dword v252, v254, s[14:15]
	global_load_dword v253, v254, s[14:15] offset:128
	v_and_b32_e32 v220, 63, v181
	v_lshrrev_b32_e32 v221, 6, v181
	v_lshrrev_b32_e32 v222, 3, v220
	v_readfirstlane_b32 s13, v221
	v_and_b32_e32 v223, 7, v220
	v_bfe_u32 v224, v220, 4, 2
	v_xor_b32_e32 v223, v223, v224
	v_lshlrev_b32_e32 v223, 4, v223
	v_and_b32_e32 v224, 1, v221
	v_lshrrev_b32_e32 v225, 1, v221
	v_lshlrev_b32_e32 v224, 5, v224
	v_lshl_add_u32 v224, v225, 7, v224
	v_add_u32_e32 v224, v224, v222
	v_lshl_add_u32 v225, v221, 5, v222
	v_lshl_or_b32 v210, v224, 11, v223
	v_lshl_or_b32 v216, v225, 11, v223
	v_xor_b32_e32 v224, 64, v210
	v_xor_b32_e32 v225, 64, v216
	v_add_u32_e32 v211, 0x3c00, v224
	v_add_u32_e32 v217, 0x3c00, v225
	v_add_u32_e32 v212, 0x7800, v210
	v_add_u32_e32 v218, 0x7800, v216
	v_add_u32_e32 v213, 0xb400, v224
	v_add_u32_e32 v219, 0xb400, v225
	v_and_b32_e32 v222, 31, v220
	v_lshrrev_b32_e32 v223, 5, v220
	v_bfe_u32 v224, v220, 1, 3
	v_xor_b32_e32 v223, v223, v224
	v_lshlrev_b32_e32 v223, 4, v223
	v_lshrrev_b32_e32 v224, 1, v221
	v_and_b32_e32 v225, 1, v221
	v_lshl_add_u32 v224, v224, 6, v222
	v_lshl_add_u32 v225, v225, 6, v222
	v_lshl_or_b32 v202, v224, 7, v223
	v_lshl_or_b32 v206, v225, 7, v223
	v_xor_b32_e32 v203, 32, v202
	v_xor_b32_e32 v207, 32, v206
	v_xor_b32_e32 v204, 64, v202
	v_xor_b32_e32 v208, 64, v206
	v_xor_b32_e32 v205, 96, v202
	v_xor_b32_e32 v209, 96, v206
	s_lshl_b32 s13, s13, 12
	s_sub_u32 s10, s4, 0x80
	s_subb_u32 s11, s5, 0
	s_add_u32 s8, s2, 0x1ff80
	s_addc_u32 s9, s3, 0
	s_sub_u32 s6, s2, 0x80
	s_subb_u32 s7, s3, 0
	s_mov_b32 s12, 0
	v_mov_b32_e32 v112, 0
	v_mov_b32_e32 v113, 0
	v_mov_b32_e32 v114, 0
	v_mov_b32_e32 v115, 0
	v_mov_b32_e32 v116, 0
	v_mov_b32_e32 v117, 0
	v_mov_b32_e32 v118, 0
	v_mov_b32_e32 v119, 0
	v_mov_b32_e32 v120, 0
	v_mov_b32_e32 v121, 0
	v_mov_b32_e32 v122, 0
	v_mov_b32_e32 v123, 0
	v_mov_b32_e32 v124, 0
	v_mov_b32_e32 v125, 0
	v_mov_b32_e32 v126, 0
	v_mov_b32_e32 v127, 0
	v_mov_b32_e32 v48, 0
	v_mov_b32_e32 v49, 0
	v_mov_b32_e32 v50, 0
	v_mov_b32_e32 v51, 0
	v_mov_b32_e32 v52, 0
	v_mov_b32_e32 v53, 0
	v_mov_b32_e32 v54, 0
	v_mov_b32_e32 v55, 0
	v_mov_b32_e32 v56, 0
	v_mov_b32_e32 v57, 0
	v_mov_b32_e32 v58, 0
	v_mov_b32_e32 v59, 0
	v_mov_b32_e32 v60, 0
	v_mov_b32_e32 v61, 0
	v_mov_b32_e32 v62, 0
	v_mov_b32_e32 v63, 0
	v_mov_b32_e32 v96, 0
	v_mov_b32_e32 v97, 0
	v_mov_b32_e32 v98, 0
	v_mov_b32_e32 v99, 0
	v_mov_b32_e32 v100, 0
	v_mov_b32_e32 v101, 0
	v_mov_b32_e32 v102, 0
	v_mov_b32_e32 v103, 0
	v_mov_b32_e32 v104, 0
	v_mov_b32_e32 v105, 0
	v_mov_b32_e32 v106, 0
	v_mov_b32_e32 v107, 0
	v_mov_b32_e32 v108, 0
	v_mov_b32_e32 v109, 0
	v_mov_b32_e32 v110, 0
	v_mov_b32_e32 v111, 0
	v_mov_b32_e32 v32, 0
	v_mov_b32_e32 v33, 0
	v_mov_b32_e32 v34, 0
	v_mov_b32_e32 v35, 0
	v_mov_b32_e32 v36, 0
	v_mov_b32_e32 v37, 0
	v_mov_b32_e32 v38, 0
	v_mov_b32_e32 v39, 0
	v_mov_b32_e32 v40, 0
	v_mov_b32_e32 v41, 0
	v_mov_b32_e32 v42, 0
	v_mov_b32_e32 v43, 0
	v_mov_b32_e32 v44, 0
	v_mov_b32_e32 v45, 0
	v_mov_b32_e32 v46, 0
	v_mov_b32_e32 v47, 0
	v_mov_b32_e32 v80, 0
	v_mov_b32_e32 v81, 0
	v_mov_b32_e32 v82, 0
	v_mov_b32_e32 v83, 0
	v_mov_b32_e32 v84, 0
	v_mov_b32_e32 v85, 0
	v_mov_b32_e32 v86, 0
	v_mov_b32_e32 v87, 0
	v_mov_b32_e32 v88, 0
	v_mov_b32_e32 v89, 0
	v_mov_b32_e32 v90, 0
	v_mov_b32_e32 v91, 0
	v_mov_b32_e32 v92, 0
	v_mov_b32_e32 v93, 0
	v_mov_b32_e32 v94, 0
	v_mov_b32_e32 v95, 0
	v_mov_b32_e32 v16, 0
	v_mov_b32_e32 v17, 0
	v_mov_b32_e32 v18, 0
	v_mov_b32_e32 v19, 0
	v_mov_b32_e32 v20, 0
	v_mov_b32_e32 v21, 0
	v_mov_b32_e32 v22, 0
	v_mov_b32_e32 v23, 0
	v_mov_b32_e32 v24, 0
	v_mov_b32_e32 v25, 0
	v_mov_b32_e32 v26, 0
	v_mov_b32_e32 v27, 0
	v_mov_b32_e32 v28, 0
	v_mov_b32_e32 v29, 0
	v_mov_b32_e32 v30, 0
	v_mov_b32_e32 v31, 0
	v_mov_b32_e32 v64, 0
	v_mov_b32_e32 v65, 0
	v_mov_b32_e32 v66, 0
	v_mov_b32_e32 v67, 0
	v_mov_b32_e32 v68, 0
	v_mov_b32_e32 v69, 0
	v_mov_b32_e32 v70, 0
	v_mov_b32_e32 v71, 0
	v_mov_b32_e32 v72, 0
	v_mov_b32_e32 v73, 0
	v_mov_b32_e32 v74, 0
	v_mov_b32_e32 v75, 0
	v_mov_b32_e32 v76, 0
	v_mov_b32_e32 v77, 0
	v_mov_b32_e32 v78, 0
	v_mov_b32_e32 v79, 0
	v_mov_b32_e32 v0, 0
	v_mov_b32_e32 v1, 0
	v_mov_b32_e32 v2, 0
	v_mov_b32_e32 v3, 0
	v_mov_b32_e32 v4, 0
	v_mov_b32_e32 v5, 0
	v_mov_b32_e32 v6, 0
	v_mov_b32_e32 v7, 0
	v_mov_b32_e32 v8, 0
	v_mov_b32_e32 v9, 0
	v_mov_b32_e32 v10, 0
	v_mov_b32_e32 v11, 0
	v_mov_b32_e32 v12, 0
	v_mov_b32_e32 v13, 0
	v_mov_b32_e32 v14, 0
	v_mov_b32_e32 v15, 0
	s_setprio 2
	s_waitcnt lgkmcnt(0)
	s_barrier
	s_add_u32 s10, s10, 0x80
	s_addc_u32 s11, s11, 0
	s_add_u32 m0, s13, 0
	s_nop 0
	global_load_lds_dwordx4 v216, s[10:11]
	global_load_lds_dwordx4 v217, s[10:11] offset:1024
	global_load_lds_dwordx4 v218, s[10:11] offset:2048
	global_load_lds_dwordx4 v219, s[10:11] offset:3072
	s_add_u32 s6, s6, 0x80
	s_addc_u32 s7, s7, 0
	s_add_u32 m0, s13, 32768
	s_nop 0
	global_load_lds_dwordx4 v210, s[6:7]
	global_load_lds_dwordx4 v211, s[6:7] offset:1024
	global_load_lds_dwordx4 v212, s[6:7] offset:2048
	global_load_lds_dwordx4 v213, s[6:7] offset:3072

; #define GLOAD(dst, kt_) _Pragma("unroll") for (int i = 0; i < NCH; ++i) { dst[i] = (i < NCHW) ? ldw(i, tid >> 3, (kt_) * 64 + (tid & 7) * 8) : ldx(i - NCHW, tid >> 3, (kt_) * 64 + (tid & 7) * 8); }
; #define LSTORE(src, base) _Pragma("unroll") for (int i = 0; i < NCH; ++i) { const int c = tid + 256 * i; *(u32x4*)((base) + (c >> 3) * 144 + (c & 7) * 16) = src[i]; }
; template <int WGN, int INS, int IMS, bool DB, class LdW, class LdX>
; DI void gemm_core(f32x16 (&acc)[INS][IMS], const int KT, LdW ldw, LdX ldx, char* lds, const int tid) {
;     ...
;     for (int kt = 0; kt < KT; kt += 2) {
;       if (kt + 2 < KT) { GLOAD(preA, kt + 2) }
;       COMPUTE_PIPE(lds)
;       LSTORE(preB, lds + BUFB)
;       __syncthreads();
;       if (kt + 3 < KT) { GLOAD(preB, kt + 3) }
;       COMPUTE_PIPE(lds + BUFB)
;       if (kt + 2 < KT) { LSTORE(preA, lds) }
;       __syncthreads();
;     }
; template <int NTW>
; DI void inproj_tile(const Params& p, int l, int mt, int ntile, char* lds) {
;     ...
;   __syncthreads();
; #pragma unroll
;   for (int im = 0; im < 2; ++im) {
;     const int tl = wm * 64 + im * 32 + l31;
;     const float r = rn[(size_t)mt * 128 + tl];
; #pragma unroll
;     for (int in = 0; in < NTW; ++in)
; #pragma unroll
;       for (int g = 0; g < 4; ++g) {
;         const int n = wn * 32 * NTW + in * 32 + 8 * g + 4 * hi;
;         u32x2 o; o[0] = pk2(acc[in][im][4 * g] * r, acc[in][im][4 * g + 1] * r); o[1] = pk2(acc[in][im][4 * g + 2] * r, acc[in][im][4 * g + 3] * r);
;         *(u32x2*)(lds + tl * RS + n * 2) = o;
;       }
;   }
.Lgb_p1c:
	s_waitcnt lgkmcnt(6)
	v_mfma_f32_32x32x16_bf16 v[80:95], v[128:131], v[160:163], v[80:95]
	v_mfma_f32_32x32x16_bf16 v[16:31], v[128:131], v[236:239], v[16:31]
	v_mfma_f32_32x32x16_bf16 v[64:79], v[144:147], v[160:163], v[64:79]
	v_mfma_f32_32x32x16_bf16 v[0:15], v[144:147], v[236:239], v[0:15]
	s_waitcnt lgkmcnt(4)
	v_mfma_f32_32x32x16_bf16 v[80:95], v[132:135], v[164:167], v[80:95]
	v_mfma_f32_32x32x16_bf16 v[16:31], v[132:135], v[240:243], v[16:31]
	v_mfma_f32_32x32x16_bf16 v[64:79], v[148:151], v[164:167], v[64:79]
	v_mfma_f32_32x32x16_bf16 v[0:15], v[148:151], v[240:243], v[0:15]
	s_waitcnt lgkmcnt(2)
	v_mfma_f32_32x32x16_bf16 v[80:95], v[136:139], v[168:171], v[80:95]
	v_mfma_f32_32x32x16_bf16 v[16:31], v[136:139], v[244:247], v[16:31]
	v_mfma_f32_32x32x16_bf16 v[64:79], v[152:155], v[168:171], v[64:79]
	v_mfma_f32_32x32x16_bf16 v[0:15], v[152:155], v[244:247], v[0:15]
	s_waitcnt lgkmcnt(0)
	v_mfma_f32_32x32x16_bf16 v[80:95], v[140:143], v[172:175], v[80:95]
	v_mfma_f32_32x32x16_bf16 v[16:31], v[140:143], v[248:251], v[16:31]
	v_mfma_f32_32x32x16_bf16 v[64:79], v[156:159], v[172:175], v[64:79]
	v_mfma_f32_32x32x16_bf16 v[0:15], v[156:159], v[248:251], v[0:15]
	s_add_i32 s12, s12, 1
	s_cmp_lg_u32 s12, 8
	s_cbranch_scc1 .Lgb_loop
	s_nop 15
	s_setprio 0
	s_barrier
	s_add_u32 s2, s27, 0x4a40000
	s_addc_u32 s3, s37, 0
	s_lshl_b64 s[0:1], s[0:1], 1
	s_add_u32 s0, s27, s0
	s_addc_u32 s1, s37, s1
	s_add_u32 s0, s0, 0x4a50000
	s_addc_u32 s1, s1, 0
	v_and_b32_e32 v128, 0x7fffff80, v181
	v_and_or_b32 v129, v185, 4, v128
	v_or_b32_e32 v128, s80, v183
	v_lshlrev_b32_e32 v132, 2, v128
	v_mov_b32_e32 v128, v252
	s_waitcnt vmcnt(0)
	s_nop 2
	v_mul_f32_e64 v112, v112, v128
	v_mul_f32_e64 v113, v113, v128
	v_cvt_pk_bf16_f32 v130, v112, v113
	v_mul_f32_e64 v112, v114, v128
	v_mul_f32_e64 v113, v115, v128
	v_mul_f32_e64 v96, v96, v128
	v_mul_f32_e64 v97, v97, v128
	v_cvt_pk_bf16_f32 v131, v112, v113
	v_lshlrev_b32_e32 v112, 1, v129
	v_mad_u32_u24 v112, v183, s73, v112
	v_pk_mul_f32 v[98:99], v[98:99], v[128:129] op_sel_hi:[1,0]
	s_nop 2
	v_pk_mul_f32 v[64:65], v[64:65], v[128:129] op_sel_hi:[1,0]
	v_pk_mul_f32 v[66:67], v[66:67], v[128:129] op_sel_hi:[1,0]
	v_cvt_pk_bf16_f32 v64, v64, v65
	v_cvt_pk_bf16_f32 v65, v66, v67
	v_pk_mul_f32 v[66:67], v[68:69], v[128:129] op_sel_hi:[1,0]
	v_pk_mul_f32 v[68:69], v[70:71], v[128:129] op_sel_hi:[1,0]
	v_cvt_pk_bf16_f32 v66, v66, v67
	v_cvt_pk_bf16_f32 v67, v68, v69
	ds_write2_b64 v112, v[64:65], v[66:67] offset0:24 offset1:26
	v_pk_mul_f32 v[64:65], v[72:73], v[128:129] op_sel_hi:[1,0]
	v_pk_mul_f32 v[66:67], v[74:75], v[128:129] op_sel_hi:[1,0]
	v_cvt_pk_bf16_f32 v64, v64, v65
	v_cvt_pk_bf16_f32 v65, v66, v67
	v_pk_mul_f32 v[66:67], v[76:77], v[128:129] op_sel_hi:[1,0]
	v_pk_mul_f32 v[68:69], v[78:79], v[128:129] op_sel_hi:[1,0]
	v_cvt_pk_bf16_f32 v66, v66, v67
	v_cvt_pk_bf16_f32 v67, v68, v69
	ds_write2_b64 v112, v[64:65], v[66:67] offset0:28 offset1:30
	v_or_b32_e32 v64, 0x80, v132
	v_mov_b32_e32 v64, v253
	v_mul_f32_e64 v114, v116, v128
	v_mul_f32_e64 v115, v117, v128
	v_mul_f32_e64 v116, v118, v128
	v_mul_f32_e64 v117, v119, v128
	v_cvt_pk_bf16_f32 v96, v96, v97
	v_cvt_pk_bf16_f32 v97, v98, v99
	v_pk_mul_f32 v[98:99], v[100:101], v[128:129] op_sel_hi:[1,0]
	v_pk_mul_f32 v[100:101], v[102:103], v[128:129] op_sel_hi:[1,0]
	v_cvt_pk_bf16_f32 v114, v114, v115
	s_nop 1
	v_mul_f32_e64 v80, v80, v128
	v_mul_f32_e64 v81, v81, v128
	v_mul_f32_e64 v82, v82, v128
	v_mul_f32_e64 v83, v83, v128
	v_cvt_pk_bf16_f32 v80, v80, v81
	v_cvt_pk_bf16_f32 v81, v82, v83
	v_pk_mul_f32 v[82:83], v[84:85], v[128:129] op_sel_hi:[1,0]
	v_pk_mul_f32 v[84:85], v[86:87], v[128:129] op_sel_hi:[1,0]
	v_cvt_pk_bf16_f32 v115, v116, v117
	v_cvt_pk_bf16_f32 v98, v98, v99
	v_cvt_pk_bf16_f32 v99, v100, v101
	v_cvt_pk_bf16_f32 v82, v82, v83
	v_cvt_pk_bf16_f32 v83, v84, v85
	ds_write2_b64 v112, v[130:131], v[114:115] offset1:2
	v_pk_mul_f32 v[114:115], v[120:121], v[128:129] op_sel_hi:[1,0]
	v_pk_mul_f32 v[116:117], v[122:123], v[128:129] op_sel_hi:[1,0]
	ds_write2_b64 v112, v[96:97], v[98:99] offset0:8 offset1:10
	v_pk_mul_f32 v[96:97], v[104:105], v[128:129] op_sel_hi:[1,0]
	v_pk_mul_f32 v[98:99], v[106:107], v[128:129] op_sel_hi:[1,0]
	ds_write2_b64 v112, v[80:81], v[82:83] offset0:16 offset1:18
	v_pk_mul_f32 v[80:81], v[88:89], v[128:129] op_sel_hi:[1,0]
	v_pk_mul_f32 v[82:83], v[90:91], v[128:129] op_sel_hi:[1,0]
	v_cvt_pk_bf16_f32 v114, v114, v115
	v_cvt_pk_bf16_f32 v115, v116, v117
	v_pk_mul_f32 v[116:117], v[124:125], v[128:129] op_sel_hi:[1,0]
	v_pk_mul_f32 v[118:119], v[126:127], v[128:129] op_sel_hi:[1,0]
	v_cvt_pk_bf16_f32 v96, v96, v97
	v_cvt_pk_bf16_f32 v97, v98, v99
	v_pk_mul_f32 v[98:99], v[108:109], v[128:129] op_sel_hi:[1,0]
	v_pk_mul_f32 v[100:101], v[110:111], v[128:129] op_sel_hi:[1,0]
	v_cvt_pk_bf16_f32 v80, v80, v81
	v_cvt_pk_bf16_f32 v81, v82, v83
	v_pk_mul_f32 v[82:83], v[92:93], v[128:129] op_sel_hi:[1,0]
	v_pk_mul_f32 v[84:85], v[94:95], v[128:129] op_sel_hi:[1,0]
	v_cvt_pk_bf16_f32 v116, v116, v117
	v_cvt_pk_bf16_f32 v117, v118, v119
	v_cvt_pk_bf16_f32 v98, v98, v99
	v_cvt_pk_bf16_f32 v99, v100, v101
	v_cvt_pk_bf16_f32 v82, v82, v83
	v_cvt_pk_bf16_f32 v83, v84, v85
	s_mov_b32 s2, 0
	ds_write2_b64 v112, v[114:115], v[116:117] offset0:4 offset1:6
	ds_write2_b64 v112, v[96:97], v[98:99] offset0:12 offset1:14
	ds_write2_b64 v112, v[80:81], v[82:83] offset0:20 offset1:22
	s_waitcnt vmcnt(0)
; template <int NTW>
; DI void inproj_tile(const Params& p, int l, int mt, int ntile, char* lds) {
;     ...
; #pragma unroll
;   for (int im = 0; im < 2; ++im) {
;     const int tl = wm * 64 + im * 32 + l31;
;     const float r = rn[(size_t)mt * 128 + tl];
; #pragma unroll
;     for (int in = 0; in < NTW; ++in)
; #pragma unroll
;       for (int g = 0; g < 4; ++g) {
;         const int n = wn * 32 * NTW + in * 32 + 8 * g + 4 * hi;
;         u32x2 o; o[0] = pk2(acc[in][im][4 * g] * r, acc[in][im][4 * g + 1] * r); o[1] = pk2(acc[in][im][4 * g + 2] * r, acc[in][im][4 * g + 3] * r);
;         *(u32x2*)(lds + tl * RS + n * 2) = o;
;       }
;   }
;   __syncthreads();
	v_pk_mul_f32 v[48:49], v[48:49], v[64:65] op_sel_hi:[1,0]
	v_pk_mul_f32 v[50:51], v[50:51], v[64:65] op_sel_hi:[1,0]
	v_pk_mul_f32 v[32:33], v[32:33], v[64:65] op_sel_hi:[1,0]
	v_pk_mul_f32 v[34:35], v[34:35], v[64:65] op_sel_hi:[1,0]
	v_pk_mul_f32 v[16:17], v[16:17], v[64:65] op_sel_hi:[1,0]
	v_pk_mul_f32 v[18:19], v[18:19], v[64:65] op_sel_hi:[1,0]
	v_pk_mul_f32 v[0:1], v[0:1], v[64:65] op_sel_hi:[1,0]
	v_pk_mul_f32 v[2:3], v[2:3], v[64:65] op_sel_hi:[1,0]
	v_cvt_pk_bf16_f32 v48, v48, v49
	v_cvt_pk_bf16_f32 v49, v50, v51
	v_pk_mul_f32 v[50:51], v[52:53], v[64:65] op_sel_hi:[1,0]
	v_pk_mul_f32 v[52:53], v[54:55], v[64:65] op_sel_hi:[1,0]
	v_cvt_pk_bf16_f32 v32, v32, v33
	v_cvt_pk_bf16_f32 v33, v34, v35
	v_pk_mul_f32 v[34:35], v[36:37], v[64:65] op_sel_hi:[1,0]
	v_pk_mul_f32 v[36:37], v[38:39], v[64:65] op_sel_hi:[1,0]
	v_cvt_pk_bf16_f32 v16, v16, v17
	v_cvt_pk_bf16_f32 v17, v18, v19
	v_pk_mul_f32 v[18:19], v[20:21], v[64:65] op_sel_hi:[1,0]
	v_pk_mul_f32 v[20:21], v[22:23], v[64:65] op_sel_hi:[1,0]
	v_cvt_pk_bf16_f32 v0, v0, v1
	v_cvt_pk_bf16_f32 v1, v2, v3
	v_pk_mul_f32 v[2:3], v[4:5], v[64:65] op_sel_hi:[1,0]
	v_pk_mul_f32 v[4:5], v[6:7], v[64:65] op_sel_hi:[1,0]
	v_cvt_pk_bf16_f32 v50, v50, v51
	v_cvt_pk_bf16_f32 v51, v52, v53
	v_add_u32_e32 v54, 0x4000, v112
	v_cvt_pk_bf16_f32 v34, v34, v35
	v_cvt_pk_bf16_f32 v35, v36, v37
	v_cvt_pk_bf16_f32 v18, v18, v19
	v_cvt_pk_bf16_f32 v19, v20, v21
	v_cvt_pk_bf16_f32 v2, v2, v3
	v_cvt_pk_bf16_f32 v3, v4, v5
	ds_write2_b64 v54, v[48:49], v[50:51] offset0:64 offset1:66
	v_pk_mul_f32 v[48:49], v[56:57], v[64:65] op_sel_hi:[1,0]
	v_pk_mul_f32 v[50:51], v[58:59], v[64:65] op_sel_hi:[1,0]
	ds_write2_b64 v54, v[32:33], v[34:35] offset0:72 offset1:74
	v_pk_mul_f32 v[32:33], v[40:41], v[64:65] op_sel_hi:[1,0]
	v_pk_mul_f32 v[34:35], v[42:43], v[64:65] op_sel_hi:[1,0]
	ds_write2_b64 v54, v[16:17], v[18:19] offset0:80 offset1:82
	v_pk_mul_f32 v[16:17], v[24:25], v[64:65] op_sel_hi:[1,0]
	v_pk_mul_f32 v[18:19], v[26:27], v[64:65] op_sel_hi:[1,0]
	ds_write2_b64 v54, v[0:1], v[2:3] offset0:88 offset1:90
	v_pk_mul_f32 v[0:1], v[8:9], v[64:65] op_sel_hi:[1,0]
	v_pk_mul_f32 v[2:3], v[10:11], v[64:65] op_sel_hi:[1,0]
	v_cvt_pk_bf16_f32 v48, v48, v49
	v_cvt_pk_bf16_f32 v49, v50, v51
	v_pk_mul_f32 v[50:51], v[60:61], v[64:65] op_sel_hi:[1,0]
	v_pk_mul_f32 v[52:53], v[62:63], v[64:65] op_sel_hi:[1,0]
	v_cvt_pk_bf16_f32 v32, v32, v33
	v_cvt_pk_bf16_f32 v33, v34, v35
	v_pk_mul_f32 v[34:35], v[44:45], v[64:65] op_sel_hi:[1,0]
	v_pk_mul_f32 v[36:37], v[46:47], v[64:65] op_sel_hi:[1,0]
	v_cvt_pk_bf16_f32 v16, v16, v17
	v_cvt_pk_bf16_f32 v17, v18, v19
	v_pk_mul_f32 v[18:19], v[28:29], v[64:65] op_sel_hi:[1,0]
	v_pk_mul_f32 v[20:21], v[30:31], v[64:65] op_sel_hi:[1,0]
	v_cvt_pk_bf16_f32 v0, v0, v1
	v_cvt_pk_bf16_f32 v1, v2, v3
	v_pk_mul_f32 v[2:3], v[12:13], v[64:65] op_sel_hi:[1,0]
	v_pk_mul_f32 v[4:5], v[14:15], v[64:65] op_sel_hi:[1,0]
	v_cvt_pk_bf16_f32 v50, v50, v51
	v_cvt_pk_bf16_f32 v51, v52, v53
	v_cvt_pk_bf16_f32 v34, v34, v35
	v_cvt_pk_bf16_f32 v35, v36, v37
	v_cvt_pk_bf16_f32 v18, v18, v19
	v_cvt_pk_bf16_f32 v19, v20, v21
	v_cvt_pk_bf16_f32 v2, v2, v3
	v_cvt_pk_bf16_f32 v3, v4, v5
	ds_write2_b64 v54, v[48:49], v[50:51] offset0:68 offset1:70
	ds_write2_b64 v54, v[32:33], v[34:35] offset0:76 offset1:78
	ds_write2_b64 v54, v[16:17], v[18:19] offset0:84 offset1:86
	ds_write2_b64 v54, v[0:1], v[2:3] offset0:92 offset1:94
	s_waitcnt lgkmcnt(0)
	s_barrier
